# MIX1 queue: next item's ticket fetched at item start, atomic round trip hidden behind the item
# baseline (speedup 1.0000x reference)
.LBB0_516:
	v_readlane_b32 s14, v251, 2
	v_readlane_b32 s15, v251, 3
	s_and_saveexec_b64 s[14:15], s[14:15]
	s_cbranch_execz .Lq_skip
	v_readlane_b32 s12, v254, 58
	v_readlane_b32 s13, v254, 59
	v_mov_b32_e32 v240, 1
	s_nop 4
	global_atomic_add v240, v1, v240, s[12:13] sc0
.Lq_skip:
	s_mov_b64 exec, s[14:15]
	s_cmpk_gt_i32 s2, 0xff
	s_mov_b64 s[24:25], -1
	s_cbranch_scc0 .LBB0_642
	s_cmpk_gt_u32 s2, 0x11f
	s_cbranch_scc0 .LBB0_549
	s_cmpk_gt_u32 s2, 0x21f
	s_cbranch_scc0 .LBB0_529
	s_cmpk_gt_u32 s2, 0x29f
	s_cbranch_scc0 .LBB0_525
	s_add_i32 s24, s2, 0xfffffd60
	s_lshr_b32 s14, s24, 8
	s_bfe_u32 s3, s24, 0x70001
	s_cmp_eq_u32 s14, 1
	s_cselect_b32 s15, 2, 4
	s_cmpk_gt_u32 s24, 0xff
	s_cselect_b32 s26, s15, 0
	s_lshr_b32 s15, 0x80, s26
	s_add_i32 s15, s15, -1
	s_and_b32 s15, s15, s3
	s_waitcnt vmcnt(0)
	v_mov_b32_e32 v6, v178
	s_xor_b32 s20, s26, 7
	s_lshl_b32 s28, s15, 7
	s_lshr_b32 s27, s3, s20
	v_ashrrev_i32_e32 v7, 1, v6
	s_add_i32 s3, s28, 0xffffff80
	v_add_u32_e32 v0, s3, v7
	v_max_i32_e32 v0, 0, v0
	v_lshlrev_b32_e32 v0, s26, v0
	s_lshl_b32 s3, s24, 1
	v_add_u32_e32 v0, s27, v0
	v_mov_b64_e32 v[2:3], s[18:19]
	s_and_b32 s3, s3, 2
	v_mad_u64_u32 v[4:5], s[20:21], v0, s17, v[2:3]
	v_and_b32_e32 v8, 1, v6
	s_and_b32 s20, s24, 0xffffff00
	s_lshl_b32 s21, s3, 6
	v_lshlrev_b32_e32 v0, 6, v8
	s_or_b32 s86, s21, s20
	v_lshl_add_u64 v[4:5], v[4:5], 0, v[0:1]
	s_lshl_b64 s[20:21], s[86:87], 1
	v_lshl_add_u64 v[4:5], v[4:5], 0, s[20:21]
	s_mov_b64 s[24:25], 0x1a00
	v_lshl_add_u64 v[10:11], v[4:5], 0, s[24:25]
	v_add_co_u32_e32 v4, vcc, s85, v4
	v_ashrrev_i32_e32 v53, 6, v6
	s_nop 0
	v_addc_co_u32_e32 v5, vcc, 0, v5, vcc
	v_lshlrev_b32_e32 v43, 4, v53
	global_load_dwordx4 v[44:47], v[4:5], off offset:2560
	global_load_dwordx4 v[56:59], v[10:11], off offset:16
	global_load_dwordx4 v[66:69], v[10:11], off offset:32
	global_load_dwordx4 v[72:75], v[10:11], off offset:48
	global_load_dwordx4 v[76:79], v[10:11], off offset:1536
	global_load_dwordx4 v[80:83], v[10:11], off offset:1552
	global_load_dwordx4 v[84:87], v[10:11], off offset:1568
	global_load_dwordx4 v[88:91], v[10:11], off offset:1584
	v_and_b32_e32 v54, 15, v6
	v_add_u32_e32 v4, s28, v43
	v_or_b32_e32 v4, v4, v54
	v_lshlrev_b32_e32 v4, s26, v4
	v_bfe_u32 v70, v6, 4, 2
	v_add_u32_e32 v42, s27, v4
	v_mov_b32_e32 v49, v1
	v_lshlrev_b32_e32 v48, 4, v70
	v_mad_i64_i32 v[2:3], s[24:25], v42, s17, v[2:3]
	v_lshl_add_u64 v[2:3], v[2:3], 0, v[48:49]
	v_lshl_add_u64 v[2:3], v[2:3], 0, s[20:21]
	v_add_co_u32_e32 v4, vcc, s85, v2
	s_mov_b64 s[20:21], 0x1400
	s_nop 0
	v_addc_co_u32_e32 v5, vcc, 0, v3, vcc
	global_load_dwordx4 v[92:95], v[4:5], off offset:1024
	v_lshl_add_u64 v[2:3], v[2:3], 0, s[20:21]
	global_load_dwordx4 v[96:99], v[2:3], off offset:64
	s_movk_i32 s12, 0x90
	v_mul_lo_u32 v65, v7, s12
	v_and_b32_e32 v60, -2, v6
	v_mul_u32_u24_e32 v62, 0x4200, v8
	v_add3_u32 v49, 0, v65, v0
	v_or_b32_e32 v43, v43, v54
	v_add3_u32 v50, 0, v62, v60
	global_load_dwordx4 v[6:9], v[2:3], off offset:128
	s_nop 0
	global_load_dwordx4 v[2:5], v[2:3], off offset:192
	s_nop 0
	global_load_dwordx4 v[26:29], v[10:11], off offset:176
	global_load_dwordx4 v[22:25], v[10:11], off offset:1664
	global_load_dwordx4 v[30:33], v[10:11], off offset:160
	global_load_dwordx4 v[34:37], v[10:11], off offset:144
	global_load_dwordx4 v[38:41], v[10:11], off offset:128
	global_load_dwordx4 v[18:21], v[10:11], off offset:1680
	global_load_dwordx4 v[14:17], v[10:11], off offset:1696
	s_nop 0
	global_load_dwordx4 v[10:13], v[10:11], off offset:1712
	v_add_u32_e32 v51, 0, v48
	v_add_u32_e32 v55, 1, v53
	s_cmp_lg_u32 s15, 0
	s_cselect_b64 s[20:21], -1, 0
	v_lshlrev_b32_e32 v52, 2, v70
	v_cmp_lt_i32_e32 vcc, v186, v250
	v_cmp_lt_i32_e64 s[44:45], 7, v53
	s_or_b64 s[24:25], s[20:21], s[44:45]
	s_mul_i32 s86, s14, 0x4100
	v_readlane_b32 s14, v254, 60
	v_readlane_b32 s15, v254, 61
	v_cmp_eq_u32_e64 s[44:45], 0, v70
	s_waitcnt vmcnt(19)
	ds_write_b128 v49, v[44:47]
	s_waitcnt vmcnt(18)
	ds_write_b128 v49, v[56:59] offset:16
	s_waitcnt vmcnt(17)
	ds_write_b128 v49, v[66:69] offset:32
	s_waitcnt vmcnt(16)
	ds_write_b128 v49, v[72:75] offset:48
	s_waitcnt vmcnt(15)
	ds_write_b16 v50, v76 offset:36864
	ds_write_b16_d16_hi v50, v76 offset:37392
	ds_write_b16 v50, v77 offset:37920
	ds_write_b16_d16_hi v50, v77 offset:38448
	ds_write_b16 v50, v78 offset:38976
	ds_write_b16_d16_hi v50, v78 offset:39504
	ds_write_b16 v50, v79 offset:40032
	ds_write_b16_d16_hi v50, v79 offset:40560
	s_waitcnt vmcnt(14)
	ds_write_b16 v50, v80 offset:41088
	ds_write_b16_d16_hi v50, v80 offset:41616
	ds_write_b16 v50, v81 offset:42144
	ds_write_b16_d16_hi v50, v81 offset:42672
	ds_write_b16 v50, v82 offset:43200
	ds_write_b16_d16_hi v50, v82 offset:43728
	ds_write_b16 v50, v83 offset:44256
	ds_write_b16_d16_hi v50, v83 offset:44784
	s_waitcnt vmcnt(13)
	ds_write_b16 v50, v84 offset:45312
	ds_write_b16_d16_hi v50, v84 offset:45840
	ds_write_b16 v50, v85 offset:46368
	ds_write_b16_d16_hi v50, v85 offset:46896
	ds_write_b16 v50, v86 offset:47424
	ds_write_b16_d16_hi v50, v86 offset:47952
	ds_write_b16 v50, v87 offset:48480
	ds_write_b16_d16_hi v50, v87 offset:49008
	s_waitcnt vmcnt(12)
	ds_write_b16 v50, v88 offset:49536
	ds_write_b16_d16_hi v50, v88 offset:50064
	ds_write_b16 v50, v89 offset:50592
	ds_write_b16_d16_hi v50, v89 offset:51120
	ds_write_b16 v50, v90 offset:51648
	ds_write_b16_d16_hi v50, v90 offset:52176
	ds_write_b16 v50, v91 offset:52704
	ds_write_b16_d16_hi v50, v91 offset:53232
	v_mul_lo_u32 v69, v43, s12
	v_add_u32_e32 v43, v51, v69
	s_waitcnt lgkmcnt(0)
	s_barrier
	ds_read_b128 v[44:47], v43
	ds_read_b128 v[56:59], v43 offset:64
	s_waitcnt vmcnt(11) lgkmcnt(1)
	v_mfma_f32_16x16x32_bf16 v[44:47], v[44:47], v[92:95], 0
	v_lshl_or_b32 v43, v55, 4, v54
	v_mul_lo_u32 v68, v43, s12
	v_add_u32_e32 v43, v51, v68
	s_waitcnt vmcnt(10) lgkmcnt(0)
	v_mfma_f32_16x16x32_bf16 v[44:47], v[56:59], v[96:99], v[44:47]
	ds_read_b128 v[56:59], v43
	ds_read_b128 v[74:77], v43 offset:64
	v_add_u32_e32 v73, 2, v53
	v_lshl_or_b32 v43, v73, 4, v54
	v_mul_lo_u32 v67, v43, s12
	v_add_u32_e32 v43, v51, v67
	s_waitcnt lgkmcnt(1)
	v_mfma_f32_16x16x32_bf16 v[56:59], v[56:59], v[92:95], 0
	ds_read_b128 v[78:81], v43
	v_add_u32_e32 v66, 0x1b00, v69
	v_add_u32_e32 v72, 4, v53
	s_waitcnt lgkmcnt(1)
	v_mfma_f32_16x16x32_bf16 v[74:77], v[74:77], v[96:99], v[56:59]
	v_add_u32_e32 v63, 0x2d00, v69
	v_add_u32_e32 v50, 6, v53
	v_add_u32_e32 v49, 8, v53
	ds_read_b128 v[56:59], v43 offset:64
	s_waitcnt lgkmcnt(1)
	v_mfma_f32_16x16x32_bf16 v[78:81], v[78:81], v[92:95], 0
	v_add_u32_e32 v43, v51, v66
	v_lshlrev_b32_e32 v55, 5, v55
	s_waitcnt lgkmcnt(0)
	v_mfma_f32_16x16x32_bf16 v[78:81], v[56:59], v[96:99], v[78:81]
	ds_read_b128 v[56:59], v43
	ds_read_b128 v[82:85], v43 offset:64
	v_lshl_or_b32 v43, v72, 4, v54
	v_mul_lo_u32 v64, v43, s12
	v_add_u32_e32 v43, v51, v64
	s_waitcnt lgkmcnt(1)
	v_mfma_f32_16x16x32_bf16 v[56:59], v[56:59], v[92:95], 0
	ds_read_b128 v[86:89], v43
	s_waitcnt lgkmcnt(1)
	v_mfma_f32_16x16x32_bf16 v[82:85], v[82:85], v[96:99], v[56:59]
	s_nop 4
	ds_read_b128 v[56:59], v43 offset:64
	s_waitcnt lgkmcnt(1)
	v_mfma_f32_16x16x32_bf16 v[86:89], v[86:89], v[92:95], 0
	v_add_u32_e32 v43, v51, v63
	s_waitcnt lgkmcnt(0)
	v_mfma_f32_16x16x32_bf16 v[86:89], v[56:59], v[96:99], v[86:89]
	ds_read_b128 v[56:59], v43
	ds_read_b128 v[100:103], v43 offset:64
	v_lshl_or_b32 v43, v50, 4, v54
	v_mul_lo_u32 v61, v43, s12
	v_add_u32_e32 v43, v51, v61
	s_waitcnt lgkmcnt(1)
	v_mfma_f32_16x16x32_bf16 v[56:59], v[56:59], v[92:95], 0
	ds_read_b128 v[104:107], v43
	v_lshlrev_b32_e32 v50, 5, v50
	s_waitcnt lgkmcnt(1)
	v_mfma_f32_16x16x32_bf16 v[100:103], v[100:103], v[96:99], v[56:59]
	s_nop 3
	ds_read_b128 v[56:59], v43 offset:64
	s_waitcnt lgkmcnt(1)
	v_mfma_f32_16x16x32_bf16 v[104:107], v[104:107], v[92:95], 0
	s_waitcnt lgkmcnt(0)
	v_mfma_f32_16x16x32_bf16 v[104:107], v[56:59], v[96:99], v[104:107]
	v_add_u32_e32 v59, 0x3f00, v69
	v_add_u32_e32 v43, v51, v59
	ds_read_b128 v[108:111], v43
	ds_read_b128 v[112:115], v43 offset:64
	v_lshl_or_b32 v43, v49, 4, v54
	v_mul_lo_u32 v58, v43, s12
	v_add_u32_e32 v51, v51, v58
	ds_read_b128 v[116:119], v51
	ds_read_b128 v[120:123], v51 offset:64
	v_cndmask_b32_e32 v51, v185, v186, vcc
	v_cmp_le_u32_e32 vcc, v54, v52
	s_and_b64 s[46:47], s[24:25], vcc
	v_cndmask_b32_e64 v56, v193, v44, s[46:47]
	v_or_b32_e32 v44, 1, v52
	v_cmp_le_u32_e32 vcc, v54, v44
	s_and_b64 s[48:49], s[24:25], vcc
	v_cndmask_b32_e64 v57, v193, v45, s[48:49]
	v_or_b32_e32 v45, 2, v52
	v_cmp_le_u32_e32 vcc, v54, v45
	s_and_b64 s[50:51], s[24:25], vcc
	s_waitcnt lgkmcnt(3)
	v_mfma_f32_16x16x32_bf16 v[108:111], v[108:111], v[92:95], 0
	v_max3_f32 v44, v56, s82, v57
	v_lshlrev_b32_e32 v51, 2, v51
	v_lshlrev_b32_e32 v49, 5, v49
	s_waitcnt lgkmcnt(1)
	v_mfma_f32_16x16x32_bf16 v[90:93], v[116:119], v[92:95], 0
	v_cndmask_b32_e64 v94, v193, v46, s[50:51]
	v_or_b32_e32 v46, 3, v52
	v_cmp_le_u32_e32 vcc, v54, v46
	s_and_b64 s[54:55], s[24:25], vcc
	v_cmp_lt_i32_e32 vcc, 6, v53
	v_cndmask_b32_e64 v95, v193, v47, s[54:55]
	s_or_b64 s[52:53], s[20:21], vcc
	v_mfma_f32_16x16x32_bf16 v[108:111], v[112:115], v[96:99], v[108:111]
	v_max3_f32 v44, v44, v94, v95
	v_cmp_lt_i32_e32 vcc, 5, v53
	v_cndmask_b32_e64 v76, v193, v76, s[52:53]
	s_waitcnt lgkmcnt(0)
	v_mfma_f32_16x16x32_bf16 v[90:93], v[120:123], v[96:99], v[90:93]
	v_cndmask_b32_e64 v96, v193, v74, s[52:53]
	v_cndmask_b32_e64 v97, v193, v75, s[52:53]
	v_max3_f32 v44, v44, v96, v97
	v_cndmask_b32_e64 v77, v193, v77, s[52:53]
	s_or_b64 s[56:57], s[20:21], vcc
	v_max3_f32 v44, v44, v76, v77
	v_cndmask_b32_e64 v78, v193, v78, s[56:57]
	v_cndmask_b32_e64 v79, v193, v79, s[56:57]
	v_cmp_lt_i32_e32 vcc, 4, v53
	v_max3_f32 v44, v44, v78, v79
	v_cndmask_b32_e64 v80, v193, v80, s[56:57]
	v_cndmask_b32_e64 v81, v193, v81, s[56:57]
	s_or_b64 s[58:59], s[20:21], vcc
	v_max3_f32 v44, v44, v80, v81
	v_cndmask_b32_e64 v82, v193, v82, s[58:59]
	v_cndmask_b32_e64 v83, v193, v83, s[58:59]
	v_cmp_lt_i32_e32 vcc, 3, v53
	v_max3_f32 v44, v44, v82, v83
	v_cndmask_b32_e64 v84, v193, v84, s[58:59]
	v_cndmask_b32_e64 v85, v193, v85, s[58:59]
	s_or_b64 s[60:61], s[20:21], vcc
	v_max3_f32 v44, v44, v84, v85
	v_cndmask_b32_e64 v86, v193, v86, s[60:61]
	v_cndmask_b32_e64 v87, v193, v87, s[60:61]
	v_cmp_lt_i32_e32 vcc, 2, v53
	v_max3_f32 v44, v44, v86, v87
	v_cndmask_b32_e64 v88, v193, v88, s[60:61]
	v_cndmask_b32_e64 v89, v193, v89, s[60:61]
	s_or_b64 s[62:63], s[20:21], vcc
	v_cmp_lt_i32_e32 vcc, 1, v53
	v_max3_f32 v44, v44, v88, v89
	v_cndmask_b32_e64 v98, v193, v100, s[62:63]
	v_cndmask_b32_e64 v99, v193, v101, s[62:63]
	s_or_b64 s[64:65], s[20:21], vcc
	v_cmp_lt_i32_e32 vcc, 0, v53
	v_max3_f32 v44, v44, v98, v99
	v_cndmask_b32_e64 v100, v193, v102, s[62:63]
	v_cndmask_b32_e64 v101, v193, v103, s[62:63]
	s_or_b64 s[66:67], s[20:21], vcc
	v_cmp_lt_i32_e32 vcc, -1, v53
	v_max3_f32 v44, v44, v100, v101
	v_cndmask_b32_e64 v102, v193, v104, s[64:65]
	v_cndmask_b32_e64 v103, v193, v105, s[64:65]
	s_or_b64 s[20:21], s[20:21], vcc
	v_cmp_ge_u32_e32 vcc, v54, v52
	v_max3_f32 v44, v44, v102, v103
	v_cndmask_b32_e64 v104, v193, v106, s[64:65]
	v_cndmask_b32_e64 v105, v193, v107, s[64:65]
	s_and_b64 s[68:69], s[20:21], vcc
	v_cmp_gt_u32_e32 vcc, v54, v52
	v_max3_f32 v44, v44, v104, v105
	v_cndmask_b32_e64 v106, v193, v108, s[66:67]
	v_cndmask_b32_e64 v107, v193, v109, s[66:67]
	s_and_b64 s[70:71], s[20:21], vcc
	v_cmp_ge_u32_e32 vcc, v54, v45
	v_max3_f32 v44, v44, v106, v107
	v_cndmask_b32_e64 v108, v193, v110, s[66:67]
	v_cndmask_b32_e64 v109, v193, v111, s[66:67]
	s_and_b64 s[72:73], s[20:21], vcc
	v_cmp_ge_u32_e32 vcc, v54, v46
	v_max3_f32 v44, v44, v108, v109
	v_cndmask_b32_e64 v114, v193, v90, s[68:69]
	v_cndmask_b32_e64 v115, v193, v91, s[70:71]
	s_and_b64 s[74:75], s[20:21], vcc
	v_max3_f32 v44, v44, v114, v115
	v_cndmask_b32_e64 v75, v193, v92, s[72:73]
	v_cndmask_b32_e64 v74, v193, v93, s[74:75]
	v_max3_f32 v44, v44, v75, v74
	ds_bpermute_b32 v45, v51, v44
	v_cmp_lt_i32_e32 vcc, v191, v250
	v_lshlrev_b32_e32 v46, 3, v70
	v_ashrrev_i32_e32 v43, 31, v42
	v_cndmask_b32_e32 v47, v185, v191, vcc
	s_waitcnt lgkmcnt(0)
	v_max_f32_e32 v45, v45, v45
	v_lshlrev_b32_e32 v52, 2, v47
	v_max_f32_e32 v71, v44, v45
	ds_bpermute_b32 v90, v52, v71
	v_cmp_lt_f32_e32 vcc, s89, v56
	v_lshl_add_u64 v[42:43], v[42:43], 0, s[86:87]
	v_lshlrev_b64 v[44:45], 9, v[42:43]
	v_mov_b32_e32 v47, v1
	s_waitcnt lgkmcnt(0)
	v_max_f32_e32 v90, v90, v90
	v_max_f32_e32 v71, v71, v90
	v_sub_f32_e32 v90, v56, v71
	v_mul_f32_e32 v90, 0x3fb8aa3b, v90
	v_sub_f32_e32 v91, v57, v71
	v_exp_f32_e32 v90, v90
	v_mul_f32_e32 v91, 0x3fb8aa3b, v91
	v_exp_f32_e32 v91, v91
	v_sub_f32_e32 v92, v95, v71
	v_cndmask_b32_e32 v56, 0, v90, vcc
	v_cmp_lt_f32_e32 vcc, s89, v57
	v_add_f32_e32 v90, 0, v56
	v_mul_f32_e32 v92, 0x3fb8aa3b, v92
	v_cndmask_b32_e32 v91, 0, v91, vcc
	v_add_f32_e32 v57, v91, v90
	v_sub_f32_e32 v90, v94, v71
	v_mul_f32_e32 v90, 0x3fb8aa3b, v90
	v_exp_f32_e32 v90, v90
	v_sub_f32_e32 v93, v96, v71
	v_exp_f32_e32 v92, v92
	v_cmp_lt_f32_e32 vcc, s89, v94
	v_mul_f32_e32 v93, 0x3fb8aa3b, v93
	v_sub_f32_e32 v94, v97, v71
	v_cndmask_b32_e32 v90, 0, v90, vcc
	v_cmp_lt_f32_e32 vcc, s89, v95
	v_exp_f32_e32 v93, v93
	v_mul_f32_e32 v94, 0x3fb8aa3b, v94
	v_sub_f32_e32 v95, v76, v71
	v_exp_f32_e32 v94, v94
	v_mul_f32_e32 v95, 0x3fb8aa3b, v95
	v_exp_f32_e32 v95, v95
	v_cndmask_b32_e32 v92, 0, v92, vcc
	v_cmp_lt_f32_e32 vcc, s89, v96
	v_sub_f32_e32 v96, v77, v71
	v_mul_f32_e32 v96, 0x3fb8aa3b, v96
	v_cndmask_b32_e32 v93, 0, v93, vcc
	v_cmp_lt_f32_e32 vcc, s89, v97
	v_exp_f32_e32 v96, v96
	v_add_f32_e32 v57, v90, v57
	v_cndmask_b32_e32 v94, 0, v94, vcc
	v_cmp_lt_f32_e32 vcc, s89, v76
	v_sub_f32_e32 v76, v78, v71
	v_mul_f32_e32 v76, 0x3fb8aa3b, v76
	v_cndmask_b32_e32 v95, 0, v95, vcc
	v_cmp_lt_f32_e32 vcc, s89, v77
	v_sub_f32_e32 v77, v79, v71
	v_exp_f32_e32 v76, v76
	v_mul_f32_e32 v77, 0x3fb8aa3b, v77
	v_exp_f32_e32 v77, v77
	v_cndmask_b32_e32 v96, 0, v96, vcc
	v_cmp_lt_f32_e32 vcc, s89, v78
	v_add_f32_e32 v57, v92, v57
	v_add_f32_e32 v57, v93, v57
	v_cndmask_b32_e32 v116, 0, v76, vcc
	v_cmp_lt_f32_e32 vcc, s89, v79
	v_sub_f32_e32 v76, v80, v71
	v_mul_f32_e32 v76, 0x3fb8aa3b, v76
	v_cndmask_b32_e32 v117, 0, v77, vcc
	v_sub_f32_e32 v77, v81, v71
	v_exp_f32_e32 v76, v76
	v_mul_f32_e32 v77, 0x3fb8aa3b, v77
	v_exp_f32_e32 v77, v77
	v_cmp_lt_f32_e32 vcc, s89, v80
	v_add_f32_e32 v57, v94, v57
	v_add_f32_e32 v57, v95, v57
	v_cndmask_b32_e32 v118, 0, v76, vcc
	v_cmp_lt_f32_e32 vcc, s89, v81
	v_sub_f32_e32 v76, v82, v71
	v_mul_f32_e32 v76, 0x3fb8aa3b, v76
	v_cndmask_b32_e32 v119, 0, v77, vcc
	v_sub_f32_e32 v77, v83, v71
	v_exp_f32_e32 v76, v76
	v_mul_f32_e32 v77, 0x3fb8aa3b, v77
	v_exp_f32_e32 v77, v77
	v_cmp_lt_f32_e32 vcc, s89, v82
	v_add_f32_e32 v57, v96, v57
	v_add_f32_e32 v57, v116, v57
	v_cndmask_b32_e32 v120, 0, v76, vcc
	v_cmp_lt_f32_e32 vcc, s89, v83
	v_sub_f32_e32 v76, v84, v71
	v_mul_f32_e32 v76, 0x3fb8aa3b, v76
	v_cndmask_b32_e32 v121, 0, v77, vcc
	v_sub_f32_e32 v77, v85, v71
	v_exp_f32_e32 v76, v76
	v_mul_f32_e32 v77, 0x3fb8aa3b, v77
	v_exp_f32_e32 v77, v77
	v_cmp_lt_f32_e32 vcc, s89, v84
	v_add_f32_e32 v57, v117, v57
	v_add_f32_e32 v57, v118, v57
	v_cndmask_b32_e32 v122, 0, v76, vcc
	v_cmp_lt_f32_e32 vcc, s89, v85
	v_sub_f32_e32 v76, v86, v71
	v_mul_f32_e32 v76, 0x3fb8aa3b, v76
	v_cndmask_b32_e32 v123, 0, v77, vcc
	v_sub_f32_e32 v77, v87, v71
	v_exp_f32_e32 v76, v76
	v_mul_f32_e32 v77, 0x3fb8aa3b, v77
	v_exp_f32_e32 v77, v77
	v_cmp_lt_f32_e32 vcc, s89, v86
	v_add_f32_e32 v57, v119, v57
	v_add_f32_e32 v57, v120, v57
	v_cndmask_b32_e32 v124, 0, v76, vcc
	v_cmp_lt_f32_e32 vcc, s89, v87
	v_sub_f32_e32 v76, v88, v71
	v_mul_f32_e32 v76, 0x3fb8aa3b, v76
	v_cndmask_b32_e32 v125, 0, v77, vcc
	v_sub_f32_e32 v77, v89, v71
	v_exp_f32_e32 v76, v76
	v_mul_f32_e32 v77, 0x3fb8aa3b, v77
	v_exp_f32_e32 v77, v77
	v_cmp_lt_f32_e32 vcc, s89, v88
	v_add_f32_e32 v57, v121, v57
	v_add_f32_e32 v57, v122, v57
	v_cndmask_b32_e32 v126, 0, v76, vcc
	v_cmp_lt_f32_e32 vcc, s89, v89
	v_sub_f32_e32 v76, v98, v71
	v_mul_f32_e32 v76, 0x3fb8aa3b, v76
	v_cndmask_b32_e32 v127, 0, v77, vcc
	v_sub_f32_e32 v77, v99, v71
	v_exp_f32_e32 v76, v76
	v_mul_f32_e32 v77, 0x3fb8aa3b, v77
	v_exp_f32_e32 v77, v77
	v_cmp_lt_f32_e32 vcc, s89, v98
	v_add_f32_e32 v57, v123, v57
	v_add_f32_e32 v57, v124, v57
	v_cndmask_b32_e32 v128, 0, v76, vcc
	v_cmp_lt_f32_e32 vcc, s89, v99
	v_sub_f32_e32 v76, v100, v71
	v_mul_f32_e32 v76, 0x3fb8aa3b, v76
	v_cndmask_b32_e32 v129, 0, v77, vcc
	v_sub_f32_e32 v77, v101, v71
	v_exp_f32_e32 v76, v76
	v_mul_f32_e32 v77, 0x3fb8aa3b, v77
	v_exp_f32_e32 v77, v77
	v_cmp_lt_f32_e32 vcc, s89, v100
	v_add_f32_e32 v57, v125, v57
	v_add_f32_e32 v57, v126, v57
	v_cndmask_b32_e32 v130, 0, v76, vcc
	v_cmp_lt_f32_e32 vcc, s89, v101
	v_sub_f32_e32 v76, v102, v71
	v_mul_f32_e32 v76, 0x3fb8aa3b, v76
	v_cndmask_b32_e32 v131, 0, v77, vcc
	v_sub_f32_e32 v77, v103, v71
	v_exp_f32_e32 v76, v76
	v_mul_f32_e32 v77, 0x3fb8aa3b, v77
	v_exp_f32_e32 v77, v77
	v_cmp_lt_f32_e32 vcc, s89, v102
	v_add_f32_e32 v57, v127, v57
	v_add_f32_e32 v57, v128, v57
	v_cndmask_b32_e32 v132, 0, v76, vcc
	v_cmp_lt_f32_e32 vcc, s89, v103
	v_sub_f32_e32 v76, v104, v71
	v_mul_f32_e32 v76, 0x3fb8aa3b, v76
	v_cndmask_b32_e32 v133, 0, v77, vcc
	v_sub_f32_e32 v77, v105, v71
	v_exp_f32_e32 v76, v76
	v_mul_f32_e32 v77, 0x3fb8aa3b, v77
	v_exp_f32_e32 v77, v77
	v_cmp_lt_f32_e32 vcc, s89, v104
	v_add_f32_e32 v57, v129, v57
	v_add_f32_e32 v57, v130, v57
	v_cndmask_b32_e32 v134, 0, v76, vcc
	v_cmp_lt_f32_e32 vcc, s89, v105
	v_sub_f32_e32 v76, v106, v71
	v_mul_f32_e32 v76, 0x3fb8aa3b, v76
	v_cndmask_b32_e32 v135, 0, v77, vcc
	v_sub_f32_e32 v77, v107, v71
	v_exp_f32_e32 v76, v76
	v_mul_f32_e32 v77, 0x3fb8aa3b, v77
	v_exp_f32_e32 v77, v77
	v_cmp_lt_f32_e32 vcc, s89, v106
	v_add_f32_e32 v57, v131, v57
	v_add_f32_e32 v57, v132, v57
	v_cndmask_b32_e32 v136, 0, v76, vcc
	v_cmp_lt_f32_e32 vcc, s89, v107
	v_sub_f32_e32 v76, v108, v71
	v_mul_f32_e32 v76, 0x3fb8aa3b, v76
	v_cndmask_b32_e32 v137, 0, v77, vcc
	v_sub_f32_e32 v77, v109, v71
	v_add_f32_e32 v57, v133, v57
	v_exp_f32_e32 v76, v76
	v_mul_f32_e32 v77, 0x3fb8aa3b, v77
	v_add_f32_e32 v57, v134, v57
	v_exp_f32_e32 v77, v77
	v_add_f32_e32 v57, v135, v57
	v_add_f32_e32 v57, v136, v57
	v_cmp_lt_f32_e32 vcc, s89, v108
	v_add_f32_e32 v57, v137, v57
	v_cvt_pk_bf16_f32 v78, v93, v94
	v_cndmask_b32_e32 v138, 0, v76, vcc
	v_cmp_lt_f32_e32 vcc, s89, v109
	v_add_f32_e32 v57, v138, v57
	v_cvt_pk_bf16_f32 v76, v56, v91
	v_cndmask_b32_e32 v139, 0, v77, vcc
	v_add_f32_e32 v140, v139, v57
	v_sub_f32_e32 v57, v114, v71
	v_mul_f32_e32 v106, 0x3fb8aa3b, v57
	v_mul_u32_u24_e32 v57, 0x210, v54
	v_add3_u32 v141, 0, v46, v57
	v_lshlrev_b32_e32 v56, 5, v53
	v_add_u32_e32 v53, v141, v56
	v_add_u32_e32 v143, 0xb000, v53
	v_cvt_pk_bf16_f32 v77, v90, v92
	v_add_u32_e32 v142, 0x9000, v53
	ds_read2_b64 v[88:91], v143 offset0:32 offset1:44
	ds_read2_b64 v[80:83], v142 offset1:12
	v_add_u32_e32 v54, v141, v55
	ds_read_b64 v[86:87], v54 offset:36864
	v_cvt_pk_bf16_f32 v79, v95, v96
	ds_read_b64 v[94:95], v54 offset:45312
	s_waitcnt lgkmcnt(3)
	v_mov_b32_e32 v92, v88
	v_mov_b32_e32 v93, v89
	ds_read_b64 v[88:89], v54 offset:53760
	ds_read_b64 v[96:97], v54 offset:62208
	v_add_u32_e32 v144, 0xd000, v53
	v_exp_f32_e32 v54, v106
	s_waitcnt lgkmcnt(4)
	v_mov_b32_e32 v84, v80
	v_mov_b32_e32 v85, v81
	ds_read2_b64 v[102:105], v144 offset0:64 offset1:76
	v_add_u32_e32 v145, 0xf000, v53
	v_cmp_lt_f32_e32 vcc, s89, v114
	ds_read2_b64 v[110:113], v145 offset0:96 offset1:108
	s_waitcnt lgkmcnt(5)
	v_mfma_f32_16x16x32_bf16 v[98:101], v[84:87], v[76:79], 0
	v_cndmask_b32_e32 v148, 0, v54, vcc
	v_lshlrev_b32_e32 v54, 5, v73
	v_add_u32_e32 v53, v141, v54
	s_waitcnt lgkmcnt(1)
	v_mov_b32_e32 v86, v102
	v_mov_b32_e32 v87, v103
	ds_read_b64 v[80:81], v53 offset:36864
	v_mfma_f32_16x16x32_bf16 v[106:109], v[92:95], v[76:79], 0
	s_waitcnt lgkmcnt(1)
	v_mov_b32_e32 v94, v110
	v_mov_b32_e32 v95, v111
	v_cvt_pk_bf16_f32 v92, v116, v117
	v_mfma_f32_16x16x32_bf16 v[84:87], v[86:89], v[76:79], 0
	ds_read_b64 v[88:89], v53 offset:45312
	ds_read_b64 v[102:103], v53 offset:53760
	ds_read_b64 v[110:111], v53 offset:62208
	v_sub_f32_e32 v53, v115, v71
	v_mul_f32_e32 v53, 0x3fb8aa3b, v53
	v_mfma_f32_16x16x32_bf16 v[76:79], v[94:97], v[76:79], 0
	v_cvt_pk_bf16_f32 v93, v118, v119
	v_cvt_pk_bf16_f32 v94, v120, v121
	v_cvt_pk_bf16_f32 v95, v122, v123
	v_exp_f32_e32 v53, v53
	v_cmp_lt_f32_e32 vcc, s89, v115
	s_waitcnt lgkmcnt(3)
	v_mfma_f32_16x16x32_bf16 v[80:83], v[80:83], v[92:95], v[98:101]
	v_add_f32_e32 v73, v148, v140
	v_cndmask_b32_e32 v140, 0, v53, vcc
	v_sub_f32_e32 v53, v75, v71
	ds_read2_b64 v[96:99], v142 offset0:20 offset1:28
	v_mul_f32_e32 v122, 0x3fb8aa3b, v53
	v_lshlrev_b32_e32 v53, 5, v72
	s_waitcnt lgkmcnt(3)
	v_mfma_f32_16x16x32_bf16 v[88:91], v[88:91], v[92:95], v[106:109]
	v_add_u32_e32 v72, v141, v53
	v_cmp_lt_f32_e32 vcc, s89, v75
	v_add_f32_e32 v73, v140, v73
	s_waitcnt lgkmcnt(2)
	v_mfma_f32_16x16x32_bf16 v[84:87], v[102:105], v[92:95], v[84:87]
	ds_read2_b64 v[100:103], v143 offset0:52 offset1:60
	ds_read_b64 v[104:105], v72 offset:36864
	s_waitcnt lgkmcnt(2)
	v_mov_b32_e32 v106, v96
	v_mov_b32_e32 v107, v97
	v_mfma_f32_16x16x32_bf16 v[76:79], v[110:113], v[92:95], v[76:79]
	v_cvt_pk_bf16_f32 v92, v124, v125
	v_cvt_pk_bf16_f32 v93, v126, v127
	v_cvt_pk_bf16_f32 v94, v128, v129
	v_cvt_pk_bf16_f32 v95, v130, v131
	ds_read_b64 v[108:109], v72 offset:45312
	ds_read2_b64 v[112:115], v144 offset0:84 offset1:92
	ds_read_b64 v[116:117], v72 offset:53760
	ds_read_b64 v[120:121], v72 offset:62208
	s_waitcnt lgkmcnt(4)
	v_mfma_f32_16x16x32_bf16 v[80:83], v[104:107], v[92:95], v[80:83]
	ds_read2_b64 v[104:107], v145 offset0:116 offset1:124
	v_exp_f32_e32 v72, v122
	v_mov_b32_e32 v110, v100
	v_mov_b32_e32 v111, v101
	s_waitcnt lgkmcnt(3)
	v_mov_b32_e32 v118, v112
	s_waitcnt lgkmcnt(0)
	v_mov_b32_e32 v122, v104
	v_add_u32_e32 v104, v141, v50
	ds_read_b64 v[96:97], v104 offset:36864
	ds_read_b64 v[100:101], v104 offset:45312
	v_mov_b32_e32 v119, v113
	v_mov_b32_e32 v123, v105
	v_mfma_f32_16x16x32_bf16 v[88:91], v[108:111], v[92:95], v[88:91]
	ds_read_b64 v[112:113], v104 offset:53760
	ds_read_b64 v[104:105], v104 offset:62208
	v_lshl_add_u64 v[44:45], s[14:15], 0, v[44:45]
	v_lshl_add_u64 v[44:45], v[44:45], 0, v[46:47]
	v_mfma_f32_16x16x32_bf16 v[84:87], v[116:119], v[92:95], v[84:87]
	s_lshl_b32 s86, s3, 7
	s_mov_b32 s12, 0xf149f2ca
	v_mfma_f32_16x16x32_bf16 v[76:79], v[120:123], v[92:95], v[76:79]
	v_cvt_pk_bf16_f32 v92, v132, v133
	v_cvt_pk_bf16_f32 v93, v134, v135
	v_cvt_pk_bf16_f32 v94, v136, v137
	v_cvt_pk_bf16_f32 v95, v138, v139
	s_waitcnt lgkmcnt(3)
	s_nop 0
	v_mfma_f32_16x16x32_bf16 v[80:83], v[96:99], v[92:95], v[80:83]
	v_cndmask_b32_e32 v96, 0, v72, vcc
	v_sub_f32_e32 v72, v74, v71
	v_mul_f32_e32 v72, 0x3fb8aa3b, v72
	v_exp_f32_e32 v72, v72
	v_cmp_lt_f32_e32 vcc, s89, v74
	v_add_f32_e32 v73, v96, v73
	s_waitcnt lgkmcnt(2)
	v_mfma_f32_16x16x32_bf16 v[88:91], v[100:103], v[92:95], v[88:91]
	v_cndmask_b32_e32 v97, 0, v72, vcc
	v_add_f32_e32 v108, v97, v73
	ds_bpermute_b32 v109, v51, v108
	s_waitcnt lgkmcnt(1)
	v_mfma_f32_16x16x32_bf16 v[72:75], v[104:107], v[92:95], v[76:79]
	s_nop 2
	v_add_u32_e32 v78, v141, v49
	v_mfma_f32_16x16x32_bf16 v[84:87], v[112:115], v[92:95], v[84:87]
	ds_read_b64 v[92:93], v78 offset:36864
	v_cvt_pk_bf16_f32 v76, v148, v140
	v_cvt_pk_bf16_f32 v77, v96, v97
	ds_read_b64 v[96:97], v78 offset:45312
	ds_read_b64 v[100:101], v78 offset:53760
	ds_read_b64 v[104:105], v78 offset:62208
	v_mov_b32_e32 v78, v1
	s_waitcnt lgkmcnt(3)
	v_mov_b32_e32 v94, v92
	v_mov_b32_e32 v95, v93
	v_mov_b32_e32 v79, v1
	s_waitcnt lgkmcnt(2)
	v_mov_b32_e32 v98, v96
	v_mov_b32_e32 v99, v97
	v_mfma_f32_16x16x32_bf16 v[80:83], v[92:95], v[76:79], v[80:83]
	v_add_f32_e32 v92, v108, v109
	ds_bpermute_b32 v93, v52, v92
	s_waitcnt lgkmcnt(2)
	v_mov_b32_e32 v102, v100
	v_mov_b32_e32 v103, v101
	s_waitcnt lgkmcnt(1)
	v_mov_b32_e32 v106, v104
	v_mov_b32_e32 v107, v105
	s_waitcnt lgkmcnt(0)
	v_add_f32_e32 v47, v92, v93
	v_div_scale_f32 v92, s[14:15], v47, v47, 1.0
	v_rcp_f32_e32 v93, v92
	v_mfma_f32_16x16x32_bf16 v[88:91], v[96:99], v[76:79], v[88:91]
	v_readlane_b32 s14, v254, 62
	v_readlane_b32 s15, v254, 63
	v_fma_f32 v70, -v92, v93, 1.0
	v_fmac_f32_e32 v93, v70, v93
	v_div_scale_f32 v70, vcc, 1.0, v47, 1.0
	v_mfma_f32_16x16x32_bf16 v[84:87], v[100:103], v[76:79], v[84:87]
	v_lshl_add_u64 v[42:43], v[42:43], 4, s[14:15]
	v_mfma_f32_16x16x32_bf16 v[72:75], v[104:107], v[76:79], v[72:75]
	v_mul_f32_e32 v76, v70, v93
	v_fma_f32 v77, -v92, v76, v70
	v_fmac_f32_e32 v76, v77, v93
	v_fma_f32 v70, -v92, v76, v70
	v_div_fmas_f32 v70, v70, v93, v76
	v_div_fixup_f32 v70, v70, v47, 1.0
	v_pk_mul_f32 v[78:79], v[70:71], v[80:81] op_sel_hi:[0,1]
	v_pk_mul_f32 v[80:81], v[70:71], v[82:83] op_sel_hi:[0,1]
	v_lshl_add_u64 v[76:77], v[44:45], 0, s[86:87]
	v_cvt_pk_bf16_f32 v78, v78, v79
	v_cvt_pk_bf16_f32 v79, v80, v81
	global_store_dwordx2 v[76:77], v[78:79], off
	v_pk_mul_f32 v[78:79], v[70:71], v[88:89] op_sel_hi:[0,1]
	v_pk_mul_f32 v[80:81], v[70:71], v[90:91] op_sel_hi:[0,1]
	v_cvt_pk_bf16_f32 v78, v78, v79
	v_cvt_pk_bf16_f32 v79, v80, v81
	global_store_dwordx2 v[76:77], v[78:79], off offset:32
	v_pk_mul_f32 v[78:79], v[70:71], v[84:85] op_sel_hi:[0,1]
	v_pk_mul_f32 v[80:81], v[70:71], v[86:87] op_sel_hi:[0,1]
	v_pk_mul_f32 v[72:73], v[70:71], v[72:73] op_sel_hi:[0,1]
	v_pk_mul_f32 v[74:75], v[70:71], v[74:75] op_sel_hi:[0,1]
	v_cvt_pk_bf16_f32 v78, v78, v79
	v_cvt_pk_bf16_f32 v79, v80, v81
	v_cvt_pk_bf16_f32 v72, v72, v73
	v_cvt_pk_bf16_f32 v73, v74, v75
	global_store_dwordx2 v[76:77], v[78:79], off offset:64
	global_store_dwordx2 v[76:77], v[72:73], off offset:96
	s_and_saveexec_b64 s[24:25], s[44:45]
	s_cbranch_execz .LBB0_522
	v_cmp_gt_f32_e32 vcc, s90, v47
	s_lshl_b32 s14, s3, 2
	s_mov_b32 s15, s87
	v_cndmask_b32_e64 v70, 0, 32, vcc
	v_ldexp_f32 v47, v47, v70
	v_log_f32_e32 v47, v47
	v_cndmask_b32_e32 v70, 0, v190, vcc
	v_mul_f32_e32 v72, 0x3f317217, v47
	v_fma_f32 v72, v47, s16, -v72
	v_fmac_f32_e32 v72, 0x3377d1cf, v47
	v_fmac_f32_e32 v72, 0x3f317217, v47
	v_cmp_lt_f32_e64 vcc, |v47|, s33
	s_nop 1
	v_cndmask_b32_e32 v47, v47, v72, vcc
	v_sub_f32_e32 v47, v47, v70
	v_add_f32_e32 v47, v71, v47
	v_lshl_add_u64 v[70:71], v[42:43], 0, s[14:15]
	global_store_dword v[70:71], v47, off

.LBB0_731:
	v_readlane_b32 s12, v251, 2
	v_readlane_b32 s13, v251, 3
	s_and_saveexec_b64 s[2:3], s[12:13]
	s_cbranch_execz .LBB0_515
	s_mov_b64 s[26:27], exec
	v_mbcnt_lo_u32_b32 v0, s26, 0
	v_mbcnt_hi_u32_b32 v0, s27, v0
	v_cmp_eq_u32_e32 vcc, 0, v0
	s_and_saveexec_b64 s[24:25], vcc
	s_cbranch_execz .LBB0_514
	s_waitcnt vmcnt(0)
	v_mov_b32_e32 v2, v240
	s_branch .LBB0_514
